# skip the grid barrier after the empty prep-b phase on odd layers
# speedup vs baseline: 1.0226x; 1.0036x over previous
.LBB0_906:
	v_readlane_b32 s0, v255, 7
	s_add_i32 s2, s0, 3
	s_cmp_gt_i32 s2, s18
	v_readlane_b32 s1, v255, 8
	s_cselect_b64 s[8:9], -1, 0
	s_cmp_lt_i32 s2, s19
	s_cselect_b64 s[0:1], -1, 0
	s_and_b64 s[8:9], s[8:9], s[0:1]
	s_andn2_b64 s[8:9], s[8:9], s[44:45]
	s_andn2_b64 vcc, exec, s[8:9]
	s_cbranch_vccnz .LBB0_960
	s_waitcnt vmcnt(0)
	s_waitcnt vmcnt(63) expcnt(7) lgkmcnt(15)
	s_barrier
	s_mov_b64 s[36:37], exec
	v_readlane_b32 s8, v252, 8
	v_readlane_b32 s9, v252, 9
	s_and_b64 s[8:9], s[36:37], s[8:9]
	s_mov_b64 exec, s[8:9]
	s_cbranch_execz .LBB0_959
	s_waitcnt vmcnt(0) expcnt(0) lgkmcnt(0)
	ds_read_b32 v3, v1
	ds_read_b32 v2, v1 offset:4
	s_waitcnt lgkmcnt(1)
	v_cmp_ne_u32_e32 vcc, 0, v3
	s_cbranch_vccnz .LBB0_923
	s_mov_b32 s8, 1
	s_branch .LBB0_911
